# gate/up row-scale: each workgroup's 11 units share 2 row-tiles, so load/reduce the sum-of-squares for those 2 tiles once instead of 11 times
# speedup vs baseline: 1.0110x; 1.0110x over previous
.LBB0_1081:
.LBB0_1082:
	s_mov_b64 s[2:3], s[84:85]
	s_mov_b32 s34, s72
	s_mov_b32 s6, s71
	s_load_dwordx2 s[12:13], s[2:3], 0x110
	v_mbcnt_lo_u32_b32 v0, -1, 0
	v_mbcnt_hi_u32_b32 v0, -1, v0
	s_getreg_b32 s2, hwreg(HW_REG_HW_ID, 0, 6)
	s_lshl_b32 s2, s2, 2
	s_and_b32 s2, s2, 0xfc
	s_add_i32 s2, s2, 0
	s_add_i32 s2, s2, 0x23400
	v_mov_b32_e32 v2, s2
	ds_read_b32 v2, v2
	v_and_b32_e32 v6, 1, v0
	s_ashr_i32 s7, s6, 31
	s_xor_b64 s[10:11], s[58:59], -1
	s_ashr_i32 s35, s34, 31
	s_waitcnt lgkmcnt(0)
	v_readfirstlane_b32 s2, v2
	v_cmp_eq_u32_e64 s[4:5], 0, v6
	s_mov_b64 s[8:9], s[6:7]
	v_lshl_add_u32 v2, s2, 6, v0
	v_ashrrev_i32_e32 v4, 1, v2
	v_ashrrev_i32_e32 v5, 31, v4
	v_lshlrev_b64 v[2:3], 7, v[4:5]
	v_lshl_add_u64 v[2:3], s[12:13], 0, v[2:3]
	v_lshlrev_b32_e32 v0, 6, v6
	v_lshl_add_u64 v[2:3], v[2:3], 0, v[0:1]
	s_mov_b64 s[2:3], 0x100000
	v_lshl_add_u64 v[2:3], v[2:3], 0, s[2:3]
	v_readlane_b32 s2, v255, 4
	s_nop 1
	v_lshl_add_u32 v0, v4, 2, s2
	s_cmp_eq_u32 s34, 0x100
	s_cbranch_scc0 .LBB0_1085
	s_mov_b32 s100, s8
	s_waitcnt lgkmcnt(0)
	s_ashr_i32 s2, s100, 31
	s_lshr_b32 s2, s2, 29
	s_add_i32 s2, s100, s2
	s_ashr_i32 s3, s2, 3
	s_and_b32 s2, s2, -8
	s_sub_i32 s2, s100, s2
	s_cmp_lt_i32 s2, 0
	s_cselect_b32 s14, s62, 0x160
	s_mul_i32 s2, s2, s14
	s_add_i32 s2, s2, s3
	s_mul_hi_i32 s3, s2, 0x2e8ba2e9
	s_lshr_b32 s14, s3, 31
	s_ashr_i32 s3, s3, 5
	s_add_i32 s3, s3, s14
	s_lshl_b32 s14, s3, 3
	s_sub_i32 s15, 0x80, s14
	s_min_i32 s15, s15, 8
	s_abs_i32 s15, s15
	v_cvt_f32_u32_e32 v4, s15
	s_sub_i32 s16, 0, s15
	s_mulk_i32 s3, 0xb0
	s_sub_i32 s2, s2, s3
	v_rcp_iflag_f32_e32 v4, v4
	s_ashr_i32 s3, s2, 31
	s_abs_i32 s2, s2
	v_mul_f32_e32 v4, 0x4f7ffffe, v4
	v_cvt_u32_f32_e32 v4, v4
	s_nop 0
	v_readfirstlane_b32 s17, v4
	s_mul_i32 s16, s16, s17
	s_mul_hi_u32 s16, s17, s16
	s_add_i32 s17, s17, s16
	s_mul_hi_u32 s16, s2, s17
	s_mul_i32 s16, s16, s15
	s_sub_i32 s2, s2, s16
	s_sub_i32 s16, s2, s15
	s_cmp_ge_u32 s2, s15
	s_cselect_b32 s2, s16, s2
	s_sub_i32 s16, s2, s15
	s_cmp_ge_u32 s2, s15
	s_cselect_b32 s2, s16, s2
	s_xor_b32 s2, s2, s3
	s_sub_i32 s2, s2, s3
	s_add_i32 s2, s14, s2
	s_ashr_i32 s3, s2, 31
	s_lshl_b64 s[2:3], s[2:3], 15
	v_lshl_add_u64 v[52:53], v[2:3], 0, s[2:3]
	global_load_dwordx4 v[20:23], v[52:53], off
	global_load_dwordx4 v[24:27], v[52:53], off offset:16
	global_load_dwordx4 v[28:31], v[52:53], off offset:32
	global_load_dwordx4 v[32:35], v[52:53], off offset:48
	s_add_i32 s100, s100, 0xa00
	s_ashr_i32 s2, s100, 31
	s_lshr_b32 s2, s2, 29
	s_add_i32 s2, s100, s2
	s_ashr_i32 s3, s2, 3
	s_and_b32 s2, s2, -8
	s_sub_i32 s2, s100, s2
	s_cmp_lt_i32 s2, 0
	s_cselect_b32 s14, s62, 0x160
	s_mul_i32 s2, s2, s14
	s_add_i32 s2, s2, s3
	s_mul_hi_i32 s3, s2, 0x2e8ba2e9
	s_lshr_b32 s14, s3, 31
	s_ashr_i32 s3, s3, 5
	s_add_i32 s3, s3, s14
	s_lshl_b32 s14, s3, 3
	s_sub_i32 s15, 0x80, s14
	s_min_i32 s15, s15, 8
	s_abs_i32 s15, s15
	v_cvt_f32_u32_e32 v4, s15
	s_sub_i32 s16, 0, s15
	s_mulk_i32 s3, 0xb0
	s_sub_i32 s2, s2, s3
	v_rcp_iflag_f32_e32 v4, v4
	s_ashr_i32 s3, s2, 31
	s_abs_i32 s2, s2
	v_mul_f32_e32 v4, 0x4f7ffffe, v4
	v_cvt_u32_f32_e32 v4, v4
	s_nop 0
	v_readfirstlane_b32 s17, v4
	s_mul_i32 s16, s16, s17
	s_mul_hi_u32 s16, s17, s16
	s_add_i32 s17, s17, s16
	s_mul_hi_u32 s16, s2, s17
	s_mul_i32 s16, s16, s15
	s_sub_i32 s2, s2, s16
	s_sub_i32 s16, s2, s15
	s_cmp_ge_u32 s2, s15
	s_cselect_b32 s2, s16, s2
	s_sub_i32 s16, s2, s15
	s_cmp_ge_u32 s2, s15
	s_cselect_b32 s2, s16, s2
	s_xor_b32 s2, s2, s3
	s_sub_i32 s2, s2, s3
	s_add_i32 s2, s14, s2
	s_ashr_i32 s3, s2, 31
	s_lshl_b64 s[2:3], s[2:3], 15
	v_lshl_add_u64 v[54:55], v[2:3], 0, s[2:3]
	global_load_dwordx4 v[36:39], v[54:55], off
	global_load_dwordx4 v[40:43], v[54:55], off offset:16
	global_load_dwordx4 v[44:47], v[54:55], off offset:32
	global_load_dwordx4 v[48:51], v[54:55], off offset:48
	s_lshr_b32 s100, s6, 3
	s_sub_i32 s100, 0xcf, s100
	s_lshr_b32 s100, s100, 5
	s_waitcnt vmcnt(4)
	v_add_f32_e32 v20, v20, v21
	v_add_f32_e32 v21, v22, v23
	v_add_f32_e32 v22, v24, v25
	v_add_f32_e32 v23, v26, v27
	v_add_f32_e32 v24, v28, v29
	v_add_f32_e32 v25, v30, v31
	v_add_f32_e32 v20, v20, v21
	v_add_f32_e32 v21, v22, v23
	v_add_f32_e32 v26, v32, v33
	v_add_f32_e32 v27, v34, v35
	v_add_f32_e32 v22, v24, v25
	v_add_f32_e32 v20, v20, v21
	v_add_f32_e32 v20, v20, v22
	v_add_f32_e32 v21, v26, v27
	v_add_f32_e32 v20, v20, v21
	ds_swizzle_b32 v21, v20 offset:swizzle(SWAP,1)
	s_waitcnt vmcnt(0)
	v_add_f32_e32 v36, v36, v37
	v_add_f32_e32 v37, v38, v39
	v_add_f32_e32 v38, v40, v41
	v_add_f32_e32 v39, v42, v43
	v_add_f32_e32 v40, v44, v45
	v_add_f32_e32 v41, v46, v47
	v_add_f32_e32 v36, v36, v37
	v_add_f32_e32 v37, v38, v39
	v_add_f32_e32 v42, v48, v49
	v_add_f32_e32 v43, v50, v51
	v_add_f32_e32 v38, v40, v41
	v_add_f32_e32 v36, v36, v37
	v_add_f32_e32 v36, v36, v38
	v_add_f32_e32 v37, v42, v43
	v_add_f32_e32 v36, v36, v37
	ds_swizzle_b32 v37, v36 offset:swizzle(SWAP,1)
	s_and_saveexec_b64 s[14:15], s[4:5]
	s_cbranch_execz .Lrs_skipw
	s_waitcnt lgkmcnt(0)
	v_add_f32_e32 v20, v20, v21
	v_fmamk_f32 v20, v20, 0x3a800000, v220
	v_mul_f32_e32 v21, 0x4b800000, v20
	v_cmp_gt_f32_e32 vcc, s33, v20
	s_nop 1
	v_cndmask_b32_e32 v20, v20, v21, vcc
	v_rsq_f32_e32 v20, v20
	s_nop 0
	v_mul_f32_e32 v21, 0x45800000, v20
	v_cndmask_b32_e32 v20, v20, v21, vcc
	v_add_f32_e32 v36, v36, v37
	v_fmamk_f32 v36, v36, 0x3a800000, v220
	v_mul_f32_e32 v37, 0x4b800000, v36
	v_cmp_gt_f32_e32 vcc, s33, v36
	s_nop 1
	v_cndmask_b32_e32 v36, v36, v37, vcc
	v_rsq_f32_e32 v36, v36
	s_nop 0
	v_mul_f32_e32 v37, 0x45800000, v36
	v_cndmask_b32_e32 v36, v36, v37, vcc
	s_cmp_gt_u32 s100, 0
	s_cselect_b64 vcc, -1, 0
	v_cndmask_b32_e32 v22, v36, v20, vcc
	ds_write_b32 v0, v22
	s_cmp_gt_u32 s100, 1
	s_cselect_b64 vcc, -1, 0
	v_cndmask_b32_e32 v22, v36, v20, vcc
	ds_write_b32 v0, v22 offset:1024
	s_cmp_gt_u32 s100, 2
	s_cselect_b64 vcc, -1, 0
	v_cndmask_b32_e32 v22, v36, v20, vcc
	ds_write_b32 v0, v22 offset:2048
	s_cmp_gt_u32 s100, 3
	s_cselect_b64 vcc, -1, 0
	v_cndmask_b32_e32 v22, v36, v20, vcc
	ds_write_b32 v0, v22 offset:3072
	s_cmp_gt_u32 s100, 4
	s_cselect_b64 vcc, -1, 0
	v_cndmask_b32_e32 v22, v36, v20, vcc
	ds_write_b32 v0, v22 offset:4096
	s_cmp_gt_u32 s100, 5
	s_cselect_b64 vcc, -1, 0
	v_cndmask_b32_e32 v22, v36, v20, vcc
	ds_write_b32 v0, v22 offset:5120
	s_cmp_gt_u32 s100, 6
	s_cselect_b64 vcc, -1, 0
	v_cndmask_b32_e32 v22, v36, v20, vcc
	ds_write_b32 v0, v22 offset:6144
	s_cmp_gt_u32 s100, 7
	s_cselect_b64 vcc, -1, 0
	v_cndmask_b32_e32 v22, v36, v20, vcc
	ds_write_b32 v0, v22 offset:7168
	s_cmp_gt_u32 s100, 8
	s_cselect_b64 vcc, -1, 0
	v_cndmask_b32_e32 v22, v36, v20, vcc
	ds_write_b32 v0, v22 offset:8192
	s_cmp_gt_u32 s100, 9
	s_cselect_b64 vcc, -1, 0
	v_cndmask_b32_e32 v22, v36, v20, vcc
	ds_write_b32 v0, v22 offset:9216
	s_cmp_gt_u32 s100, 10
	s_cselect_b64 vcc, -1, 0
	v_cndmask_b32_e32 v22, v36, v20, vcc
	ds_write_b32 v0, v22 offset:10240
